# scan: PREP regrouped by quarters (4 adjacent steps per wave, shared prefix, packed b64 column writes), all in stage S; stage X without PREP
# speedup vs baseline: 1.0514x; 1.0279x over previous
.Lsx0_a:
	v_add_u32_e32 v192, v144, v145
	v_add_u32_e32 v199, v150, v145
	s_and_saveexec_b64 s[2:3], s[54:55]
	s_cbranch_execz .Lsx0_c
	s_cmp_lg_u32 s21, 0
	s_cbranch_scc0 .Lsx0_c
	s_waitcnt lgkmcnt(0)
	v_cvt_pk_bf16_f32 v120, v116, v117
	global_store_dword v[118:119], v120, off

.LBB0_405:
	s_or_b64 exec, exec, s[2:3]
	v_lshrrev_b32_e32 v122, 6, v198
	s_nop 0
	v_readfirstlane_b32 s98, v122
	s_nop 3
	s_cmp_eq_u32 s98, 5
	s_cbranch_scc1 .Lpq0_q0
	s_cmp_eq_u32 s98, 1
	s_cbranch_scc1 .Lpq0_q1
	s_cmp_eq_u32 s98, 2
	s_cbranch_scc1 .Lpq0_q2
	s_cmp_eq_u32 s98, 3
	s_cbranch_scc1 .Lpq0_q3
	s_branch .Lpq0_end
.Lpq0_q0:
	ds_read2st64_b32 v[40:41], v143 offset0:96 offset1:97
	ds_read2st64_b32 v[42:43], v143 offset0:98 offset1:99
	ds_read2st64_b32 v[44:45], v143 offset0:100 offset1:101
	ds_read2st64_b32 v[46:47], v143 offset0:102 offset1:103
	ds_read2st64_b32 v[48:49], v143 offset0:104 offset1:105
	ds_read2st64_b32 v[50:51], v143 offset0:106 offset1:107
	ds_read2st64_b32 v[52:53], v143 offset0:108 offset1:109
	ds_read2st64_b32 v[54:55], v143 offset0:110 offset1:111
	ds_read2st64_b32 v[56:57], v143 offset0:112 offset1:113
	ds_read2st64_b32 v[58:59], v143 offset0:114 offset1:115
	ds_read2st64_b32 v[60:61], v143 offset0:116 offset1:117
	ds_read2st64_b32 v[62:63], v143 offset0:118 offset1:119
	v_lshrrev_b32_e32 v122, 1, v143
	v_mov_b32_e32 v69, 0
	s_waitcnt lgkmcnt(11)
	v_add_f32_e32 v65, v69, v41
	s_waitcnt lgkmcnt(8)
	v_add_f32_e32 v66, v65, v47
	s_waitcnt lgkmcnt(5)
	v_add_f32_e32 v67, v66, v53
	s_waitcnt lgkmcnt(2)
	v_add_f32_e32 v68, v67, v59
	v_mul_f32_e32 v79, 0xbfb8aa3b, v69
	v_exp_f32_e32 v70, v79
	v_mul_f32_e32 v80, 0xbfb8aa3b, v65
	v_exp_f32_e32 v71, v80
	v_mul_f32_e32 v79, 0x3fb8aa3b, v65
	v_exp_f32_e32 v75, v79
	v_mul_f32_e32 v80, 0xbfb8aa3b, v66
	v_exp_f32_e32 v72, v80
	v_mul_f32_e32 v79, 0x3fb8aa3b, v66
	v_exp_f32_e32 v76, v79
	v_mul_f32_e32 v80, 0xbfb8aa3b, v67
	v_exp_f32_e32 v73, v80
	v_mul_f32_e32 v79, 0x3fb8aa3b, v67
	v_exp_f32_e32 v77, v79
	v_mul_f32_e32 v80, 0xbfb8aa3b, v68
	v_exp_f32_e32 v74, v80
	v_mul_f32_e32 v79, 0x3fb8aa3b, v68
	v_exp_f32_e32 v78, v79
	s_nop 0
	v_mul_f32_e32 v81, v70, v40
	v_mul_f32_e32 v85, v75, v43
	v_mul_f32_e32 v89, v75, v42
	v_mul_f32_e32 v93, v71, v44
	v_mul_f32_e32 v82, v71, v46
	v_mul_f32_e32 v86, v76, v49
	v_mul_f32_e32 v90, v76, v48
	v_mul_f32_e32 v94, v72, v50
	v_mul_f32_e32 v83, v72, v52
	v_mul_f32_e32 v87, v77, v55
	v_mul_f32_e32 v91, v77, v54
	v_mul_f32_e32 v95, v73, v56
	v_mul_f32_e32 v84, v73, v58
	s_waitcnt lgkmcnt(1)
	v_mul_f32_e32 v88, v78, v61
	v_mul_f32_e32 v92, v78, v60
	s_waitcnt lgkmcnt(0)
	v_mul_f32_e32 v96, v74, v62
	v_cvt_pk_bf16_f32 v112, v81, v82
	v_cvt_pk_bf16_f32 v113, v83, v84
	v_cvt_pk_bf16_f32 v114, v85, v86
	v_cvt_pk_bf16_f32 v115, v87, v88
	v_cvt_pk_bf16_f32 v116, v89, v90
	v_cvt_pk_bf16_f32 v117, v91, v92
	v_cvt_pk_bf16_f32 v118, v93, v94
	v_cvt_pk_bf16_f32 v119, v95, v96
	v_cvt_pk_bf16_f32 v120, v45, v51
	v_cvt_pk_bf16_f32 v121, v57, v63
	ds_write_b16 v122, v112 offset:51456
	ds_write_b16_d16_hi v122, v112 offset:51600
	ds_write_b16 v122, v113 offset:51744
	ds_write_b16_d16_hi v122, v113 offset:51888
	ds_write_b16 v122, v114 offset:53760
	ds_write_b16_d16_hi v122, v114 offset:53904
	ds_write_b16 v122, v115 offset:54048
	ds_write_b16_d16_hi v122, v115 offset:54192
	ds_write_b16 v122, v116 offset:56064
	ds_write_b16_d16_hi v122, v116 offset:56208
	ds_write_b16 v122, v117 offset:56352
	ds_write_b16_d16_hi v122, v117 offset:56496
	ds_write_b16 v122, v118 offset:60672
	ds_write_b16_d16_hi v122, v118 offset:60816
	ds_write_b16 v122, v119 offset:60960
	ds_write_b16_d16_hi v122, v119 offset:61104
	ds_write_b64 v139, v[114:115] offset:5120
	ds_write_b64 v139, v[116:117] offset:5152
	ds_write_b64 v140, v[120:121] offset:5152
	s_branch .Lpq0_end
.Lpq0_q1:
	ds_read2st64_b32 v[26:27], v143 offset0:97 offset1:103
	ds_read2st64_b32 v[28:29], v143 offset0:109 offset1:115
	ds_read2st64_b32 v[40:41], v143 offset0:120 offset1:121
	ds_read2st64_b32 v[42:43], v143 offset0:122 offset1:123
	ds_read2st64_b32 v[44:45], v143 offset0:124 offset1:125
	ds_read2st64_b32 v[46:47], v143 offset0:126 offset1:127
	ds_read2st64_b32 v[48:49], v143 offset0:128 offset1:129
	ds_read2st64_b32 v[50:51], v143 offset0:130 offset1:131
	ds_read2st64_b32 v[52:53], v143 offset0:132 offset1:133
	ds_read2st64_b32 v[54:55], v143 offset0:134 offset1:135
	ds_read2st64_b32 v[56:57], v143 offset0:136 offset1:137
	ds_read2st64_b32 v[58:59], v143 offset0:138 offset1:139
	ds_read2st64_b32 v[60:61], v143 offset0:140 offset1:141
	ds_read2st64_b32 v[62:63], v143 offset0:142 offset1:143
	v_lshrrev_b32_e32 v122, 1, v143
	s_waitcnt lgkmcnt(13)
	v_add_f32_e32 v69, v26, v27
	s_waitcnt lgkmcnt(12)
	v_add_f32_e32 v69, v69, v28
	v_add_f32_e32 v69, v69, v29
	s_waitcnt lgkmcnt(11)
	v_add_f32_e32 v65, v69, v41
	s_waitcnt lgkmcnt(8)
	v_add_f32_e32 v66, v65, v47
	s_waitcnt lgkmcnt(5)
	v_add_f32_e32 v67, v66, v53
	s_waitcnt lgkmcnt(2)
	v_add_f32_e32 v68, v67, v59
	v_mul_f32_e32 v79, 0xbfb8aa3b, v69
	v_exp_f32_e32 v70, v79
	v_mul_f32_e32 v80, 0xbfb8aa3b, v65
	v_exp_f32_e32 v71, v80
	v_mul_f32_e32 v79, 0x3fb8aa3b, v65
	v_exp_f32_e32 v75, v79
	v_mul_f32_e32 v80, 0xbfb8aa3b, v66
	v_exp_f32_e32 v72, v80
	v_mul_f32_e32 v79, 0x3fb8aa3b, v66
	v_exp_f32_e32 v76, v79
	v_mul_f32_e32 v80, 0xbfb8aa3b, v67
	v_exp_f32_e32 v73, v80
	v_mul_f32_e32 v79, 0x3fb8aa3b, v67
	v_exp_f32_e32 v77, v79
	v_mul_f32_e32 v80, 0xbfb8aa3b, v68
	v_exp_f32_e32 v74, v80
	v_mul_f32_e32 v79, 0x3fb8aa3b, v68
	v_exp_f32_e32 v78, v79
	s_nop 0
	v_mul_f32_e32 v81, v70, v40
	v_mul_f32_e32 v85, v75, v43
	v_mul_f32_e32 v89, v75, v42
	v_mul_f32_e32 v93, v71, v44
	v_mul_f32_e32 v82, v71, v46
	v_mul_f32_e32 v86, v76, v49
	v_mul_f32_e32 v90, v76, v48
	v_mul_f32_e32 v94, v72, v50
	v_mul_f32_e32 v83, v72, v52
	v_mul_f32_e32 v87, v77, v55
	v_mul_f32_e32 v91, v77, v54
	v_mul_f32_e32 v95, v73, v56
	v_mul_f32_e32 v84, v73, v58
	s_waitcnt lgkmcnt(1)
	v_mul_f32_e32 v88, v78, v61
	v_mul_f32_e32 v92, v78, v60
	s_waitcnt lgkmcnt(0)
	v_mul_f32_e32 v96, v74, v62
	v_cvt_pk_bf16_f32 v112, v81, v82
	v_cvt_pk_bf16_f32 v113, v83, v84
	v_cvt_pk_bf16_f32 v114, v85, v86
	v_cvt_pk_bf16_f32 v115, v87, v88
	v_cvt_pk_bf16_f32 v116, v89, v90
	v_cvt_pk_bf16_f32 v117, v91, v92
	v_cvt_pk_bf16_f32 v118, v93, v94
	v_cvt_pk_bf16_f32 v119, v95, v96
	v_cvt_pk_bf16_f32 v120, v45, v51
	v_cvt_pk_bf16_f32 v121, v57, v63
	ds_write_b16 v122, v112 offset:52032
	ds_write_b16_d16_hi v122, v112 offset:52176
	ds_write_b16 v122, v113 offset:52320
	ds_write_b16_d16_hi v122, v113 offset:52464
	ds_write_b16 v122, v114 offset:54336
	ds_write_b16_d16_hi v122, v114 offset:54480
	ds_write_b16 v122, v115 offset:54624
	ds_write_b16_d16_hi v122, v115 offset:54768
	ds_write_b16 v122, v116 offset:56640
	ds_write_b16_d16_hi v122, v116 offset:56784
	ds_write_b16 v122, v117 offset:56928
	ds_write_b16_d16_hi v122, v117 offset:57072
	ds_write_b16 v122, v118 offset:61248
	ds_write_b16_d16_hi v122, v118 offset:61392
	ds_write_b16 v122, v119 offset:61536
	ds_write_b16_d16_hi v122, v119 offset:61680
	ds_write_b64 v139, v[114:115] offset:5128
	ds_write_b64 v139, v[116:117] offset:5160
	ds_write_b64 v140, v[120:121] offset:5160
	s_branch .Lpq0_end
.Lpq0_q2:
	ds_read2st64_b32 v[26:27], v143 offset0:97 offset1:103
	ds_read2st64_b32 v[28:29], v143 offset0:109 offset1:115
	ds_read2st64_b32 v[30:31], v143 offset0:121 offset1:127
	ds_read2st64_b32 v[32:33], v143 offset0:133 offset1:139
	ds_read2st64_b32 v[40:41], v143 offset0:144 offset1:145
	ds_read2st64_b32 v[42:43], v143 offset0:146 offset1:147
	ds_read2st64_b32 v[44:45], v143 offset0:148 offset1:149
	ds_read2st64_b32 v[46:47], v143 offset0:150 offset1:151
	ds_read2st64_b32 v[48:49], v143 offset0:152 offset1:153
	ds_read2st64_b32 v[50:51], v143 offset0:154 offset1:155
	ds_read2st64_b32 v[52:53], v143 offset0:156 offset1:157
	ds_read2st64_b32 v[54:55], v143 offset0:158 offset1:159
	ds_read2st64_b32 v[56:57], v143 offset0:160 offset1:161
	ds_read2st64_b32 v[58:59], v143 offset0:162 offset1:163
	ds_read2st64_b32 v[60:61], v143 offset0:164 offset1:165
	s_waitcnt lgkmcnt(14)
	ds_read2st64_b32 v[62:63], v143 offset0:166 offset1:167
	v_lshrrev_b32_e32 v122, 1, v143
	v_add_f32_e32 v69, v26, v27
	s_waitcnt lgkmcnt(14)
	v_add_f32_e32 v69, v69, v28
	v_add_f32_e32 v69, v69, v29
	s_waitcnt lgkmcnt(13)
	v_add_f32_e32 v69, v69, v30
	v_add_f32_e32 v69, v69, v31
	s_waitcnt lgkmcnt(12)
	v_add_f32_e32 v69, v69, v32
	v_add_f32_e32 v69, v69, v33
	s_waitcnt lgkmcnt(11)
	v_add_f32_e32 v65, v69, v41
	s_waitcnt lgkmcnt(8)
	v_add_f32_e32 v66, v65, v47
	s_waitcnt lgkmcnt(5)
	v_add_f32_e32 v67, v66, v53
	s_waitcnt lgkmcnt(2)
	v_add_f32_e32 v68, v67, v59
	v_mul_f32_e32 v79, 0xbfb8aa3b, v69
	v_exp_f32_e32 v70, v79
	v_mul_f32_e32 v80, 0xbfb8aa3b, v65
	v_exp_f32_e32 v71, v80
	v_mul_f32_e32 v79, 0x3fb8aa3b, v65
	v_exp_f32_e32 v75, v79
	v_mul_f32_e32 v80, 0xbfb8aa3b, v66
	v_exp_f32_e32 v72, v80
	v_mul_f32_e32 v79, 0x3fb8aa3b, v66
	v_exp_f32_e32 v76, v79
	v_mul_f32_e32 v80, 0xbfb8aa3b, v67
	v_exp_f32_e32 v73, v80
	v_mul_f32_e32 v79, 0x3fb8aa3b, v67
	v_exp_f32_e32 v77, v79
	v_mul_f32_e32 v80, 0xbfb8aa3b, v68
	v_exp_f32_e32 v74, v80
	v_mul_f32_e32 v79, 0x3fb8aa3b, v68
	v_exp_f32_e32 v78, v79
	s_nop 0
	v_mul_f32_e32 v81, v70, v40
	v_mul_f32_e32 v85, v75, v43
	v_mul_f32_e32 v89, v75, v42
	v_mul_f32_e32 v93, v71, v44
	v_mul_f32_e32 v82, v71, v46
	v_mul_f32_e32 v86, v76, v49
	v_mul_f32_e32 v90, v76, v48
	v_mul_f32_e32 v94, v72, v50
	v_mul_f32_e32 v83, v72, v52
	v_mul_f32_e32 v87, v77, v55
	v_mul_f32_e32 v91, v77, v54
	v_mul_f32_e32 v95, v73, v56
	v_mul_f32_e32 v84, v73, v58
	s_waitcnt lgkmcnt(1)
	v_mul_f32_e32 v88, v78, v61
	v_mul_f32_e32 v92, v78, v60
	s_waitcnt lgkmcnt(0)
	v_mul_f32_e32 v96, v74, v62
	v_cvt_pk_bf16_f32 v112, v81, v82
	v_cvt_pk_bf16_f32 v113, v83, v84
	v_cvt_pk_bf16_f32 v114, v85, v86
	v_cvt_pk_bf16_f32 v115, v87, v88
	v_cvt_pk_bf16_f32 v116, v89, v90
	v_cvt_pk_bf16_f32 v117, v91, v92
	v_cvt_pk_bf16_f32 v118, v93, v94
	v_cvt_pk_bf16_f32 v119, v95, v96
	v_cvt_pk_bf16_f32 v120, v45, v51
	v_cvt_pk_bf16_f32 v121, v57, v63
	ds_write_b16 v122, v112 offset:52608
	ds_write_b16_d16_hi v122, v112 offset:52752
	ds_write_b16 v122, v113 offset:52896
	ds_write_b16_d16_hi v122, v113 offset:53040
	ds_write_b16 v122, v114 offset:54912
	ds_write_b16_d16_hi v122, v114 offset:55056
	ds_write_b16 v122, v115 offset:55200
	ds_write_b16_d16_hi v122, v115 offset:55344
	ds_write_b16 v122, v116 offset:57216
	ds_write_b16_d16_hi v122, v116 offset:57360
	ds_write_b16 v122, v117 offset:57504
	ds_write_b16_d16_hi v122, v117 offset:57648
	ds_write_b16 v122, v118 offset:61824
	ds_write_b16_d16_hi v122, v118 offset:61968
	ds_write_b16 v122, v119 offset:62112
	ds_write_b16_d16_hi v122, v119 offset:62256
	ds_write_b64 v139, v[114:115] offset:5136
	ds_write_b64 v139, v[116:117] offset:5168
	ds_write_b64 v140, v[120:121] offset:5168
	s_branch .Lpq0_end
.Lpq0_q3:
	ds_read2st64_b32 v[26:27], v143 offset0:97 offset1:103
	ds_read2st64_b32 v[28:29], v143 offset0:109 offset1:115
	ds_read2st64_b32 v[30:31], v143 offset0:121 offset1:127
	ds_read2st64_b32 v[32:33], v143 offset0:133 offset1:139
	ds_read2st64_b32 v[34:35], v143 offset0:145 offset1:151
	ds_read2st64_b32 v[36:37], v143 offset0:157 offset1:163
	ds_read2st64_b32 v[40:41], v143 offset0:168 offset1:169
	ds_read2st64_b32 v[42:43], v143 offset0:170 offset1:171
	ds_read2st64_b32 v[44:45], v143 offset0:172 offset1:173
	ds_read2st64_b32 v[46:47], v143 offset0:174 offset1:175
	ds_read2st64_b32 v[48:49], v143 offset0:176 offset1:177
	ds_read2st64_b32 v[50:51], v143 offset0:178 offset1:179
	ds_read2st64_b32 v[52:53], v143 offset0:180 offset1:181
	ds_read2st64_b32 v[54:55], v143 offset0:182 offset1:183
	ds_read2st64_b32 v[56:57], v143 offset0:184 offset1:185
	s_waitcnt lgkmcnt(14)
	ds_read2st64_b32 v[58:59], v143 offset0:186 offset1:187
	s_waitcnt lgkmcnt(14)
	ds_read2st64_b32 v[60:61], v143 offset0:188 offset1:189
	s_waitcnt lgkmcnt(14)
	ds_read2st64_b32 v[62:63], v143 offset0:190 offset1:191
	v_lshrrev_b32_e32 v122, 1, v143
	v_add_f32_e32 v69, v26, v27
	v_add_f32_e32 v69, v69, v28
	v_add_f32_e32 v69, v69, v29
	v_add_f32_e32 v69, v69, v30
	v_add_f32_e32 v69, v69, v31
	s_waitcnt lgkmcnt(14)
	v_add_f32_e32 v69, v69, v32
	v_add_f32_e32 v69, v69, v33
	s_waitcnt lgkmcnt(13)
	v_add_f32_e32 v69, v69, v34
	v_add_f32_e32 v69, v69, v35
	s_waitcnt lgkmcnt(12)
	v_add_f32_e32 v69, v69, v36
	v_add_f32_e32 v69, v69, v37
	s_waitcnt lgkmcnt(11)
	v_add_f32_e32 v65, v69, v41
	s_waitcnt lgkmcnt(8)
	v_add_f32_e32 v66, v65, v47
	s_waitcnt lgkmcnt(5)
	v_add_f32_e32 v67, v66, v53
	s_waitcnt lgkmcnt(2)
	v_add_f32_e32 v68, v67, v59
	v_mul_f32_e32 v79, 0xbfb8aa3b, v69
	v_exp_f32_e32 v70, v79
	v_mul_f32_e32 v80, 0xbfb8aa3b, v65
	v_exp_f32_e32 v71, v80
	v_mul_f32_e32 v79, 0x3fb8aa3b, v65
	v_exp_f32_e32 v75, v79
	v_mul_f32_e32 v80, 0xbfb8aa3b, v66
	v_exp_f32_e32 v72, v80
	v_mul_f32_e32 v79, 0x3fb8aa3b, v66
	v_exp_f32_e32 v76, v79
	v_mul_f32_e32 v80, 0xbfb8aa3b, v67
	v_exp_f32_e32 v73, v80
	v_mul_f32_e32 v79, 0x3fb8aa3b, v67
	v_exp_f32_e32 v77, v79
	v_mul_f32_e32 v80, 0xbfb8aa3b, v68
	v_exp_f32_e32 v74, v80
	v_mul_f32_e32 v79, 0x3fb8aa3b, v68
	v_exp_f32_e32 v78, v79
	s_nop 0
	v_mul_f32_e32 v81, v70, v40
	v_mul_f32_e32 v85, v75, v43
	v_mul_f32_e32 v89, v75, v42
	v_mul_f32_e32 v93, v71, v44
	v_mul_f32_e32 v82, v71, v46
	v_mul_f32_e32 v86, v76, v49
	v_mul_f32_e32 v90, v76, v48
	v_mul_f32_e32 v94, v72, v50
	v_mul_f32_e32 v83, v72, v52
	v_mul_f32_e32 v87, v77, v55
	v_mul_f32_e32 v91, v77, v54
	v_mul_f32_e32 v95, v73, v56
	v_mul_f32_e32 v84, v73, v58
	s_waitcnt lgkmcnt(1)
	v_mul_f32_e32 v88, v78, v61
	v_mul_f32_e32 v92, v78, v60
	s_waitcnt lgkmcnt(0)
	v_mul_f32_e32 v96, v74, v62
	v_cvt_pk_bf16_f32 v112, v81, v82
	v_cvt_pk_bf16_f32 v113, v83, v84
	v_cvt_pk_bf16_f32 v114, v85, v86
	v_cvt_pk_bf16_f32 v115, v87, v88
	v_cvt_pk_bf16_f32 v116, v89, v90
	v_cvt_pk_bf16_f32 v117, v91, v92
	v_cvt_pk_bf16_f32 v118, v93, v94
	v_cvt_pk_bf16_f32 v119, v95, v96
	v_cvt_pk_bf16_f32 v120, v45, v51
	v_cvt_pk_bf16_f32 v121, v57, v63
	ds_write_b16 v122, v112 offset:53184
	ds_write_b16_d16_hi v122, v112 offset:53328
	ds_write_b16 v122, v113 offset:53472
	ds_write_b16_d16_hi v122, v113 offset:53616
	ds_write_b16 v122, v114 offset:55488
	ds_write_b16_d16_hi v122, v114 offset:55632
	ds_write_b16 v122, v115 offset:55776
	ds_write_b16_d16_hi v122, v115 offset:55920
	ds_write_b16 v122, v116 offset:57792
	ds_write_b16_d16_hi v122, v116 offset:57936
	ds_write_b16 v122, v117 offset:58080
	ds_write_b16_d16_hi v122, v117 offset:58224
	ds_write_b16 v122, v118 offset:62400
	ds_write_b16_d16_hi v122, v118 offset:62544
	ds_write_b16 v122, v119 offset:62688
	ds_write_b16_d16_hi v122, v119 offset:62832
	ds_write_b64 v139, v[114:115] offset:5144
	ds_write_b64 v139, v[116:117] offset:5176
	ds_write_b64 v140, v[120:121] offset:5176
	v_add_u32_e32 v123, 0x18e00, v143
	ds_write_b32 v123, v74
	s_branch .Lpq0_end
.Lpq0_end:
	s_waitcnt lgkmcnt(0)
	s_barrier
	v_add_u32_e32 v200, v146, v145
	v_add_u32_e32 v112, v156, v163
	ds_read_b128 v[48:51], v180
	ds_read_b128 v[52:55], v112 offset:62976
	ds_read_b128 v[56:59], v112 offset:64256
	v_sub_u32_e32 v113, v164, v143
	v_mad_u32_u24 v113, v145, 5, v113
	v_add_u32_e32 v113, 0x18d00, v113
	ds_read_b128 v[88:91], v113
	ds_read_b128 v[92:95], v113 offset:64
	v_mul_u32_u24_e32 v114, 5, v145
	v_sub_u32_e32 v114, v143, v114
	v_mul_i32_i24_e32 v114, 0x47, v114
	v_ashrrev_i32_e32 v114, 1, v114
	v_add_u32_e32 v114, v181, v114
	s_and_saveexec_b64 s[2:3], s[56:57]
	s_cbranch_execz .Lsy0_r1
	ds_read_b128 v[62:65], v175
	ds_read_b128 v[66:69], v200

.Lsy0_r2:
	s_or_b64 exec, exec, s[2:3]
	s_waitcnt lgkmcnt(2)
	v_mfma_f32_16x16x32_bf16 v[14:17], v[52:55], v[48:51], v[14:17]
	v_mfma_f32_16x16x32_bf16 v[18:21], v[56:59], v[48:51], v[18:21]
	s_and_saveexec_b64 s[2:3], s[56:57]
	s_cbranch_execz .Lsy0_m1
	s_waitcnt lgkmcnt(0)
	v_mfma_f32_16x16x32_bf16 v[22:25], v[62:65], v[66:69], v[22:25]

.Lsy0_m2:
	s_or_b64 exec, exec, s[2:3]
	s_waitcnt lgkmcnt(0)
	s_nop 1
	v_pk_mul_f32 v[14:15], v[14:15], v[88:89]
	v_pk_mul_f32 v[16:17], v[16:17], v[90:91]
	v_pk_mul_f32 v[18:19], v[18:19], v[92:93]
	v_pk_mul_f32 v[20:21], v[20:21], v[94:95]
	v_cvt_pk_bf16_f32 v116, v14, v15
	v_cvt_pk_bf16_f32 v117, v16, v17
	v_cvt_pk_bf16_f32 v118, v18, v19
	v_cvt_pk_bf16_f32 v119, v20, v21
	ds_write_b64 v114, v[116:117]
	ds_write_b64 v114, v[118:119] offset:32
	s_and_saveexec_b64 s[2:3], s[56:57]
	s_cbranch_execz .Lsy0_w1
	ds_write_b128 v179, v[22:25]

.LBB0_426:
	s_add_i32 s24, s19, -16
	s_and_b64 s[2:3], s[12:13], exec
	s_waitcnt lgkmcnt(0)
	s_barrier
	s_cselect_b32 s2, s21, s24
	s_cmpk_lt_u32 s20, 0x7f
	ds_read_b64 v[116:117], v190
	v_lshl_add_u32 v194, s2, 6, v183
	s_cselect_b64 s[2:3], -1, 0
	v_lshl_add_u64 v[118:119], v[194:195], 1, s[78:79]
	s_and_b64 s[68:69], s[54:55], s[2:3]
	s_and_saveexec_b64 s[74:75], s[54:55]
	s_cbranch_execz .Lsx1_c
	s_waitcnt lgkmcnt(0)
	v_cvt_pk_bf16_f32 v120, v116, v117
	global_store_dword v[118:119], v120, off

.LBB0_434:
	s_or_b64 exec, exec, s[74:75]
	v_lshrrev_b32_e32 v122, 6, v198
	s_nop 0
	v_readfirstlane_b32 s98, v122
	s_nop 3
	s_cmpk_lt_u32 s20, 0x7f
	s_cbranch_scc0 .Lpq1_end
	s_cmp_eq_u32 s98, 5
	s_cbranch_scc1 .Lpq1_q0
	s_cmp_eq_u32 s98, 1
	s_cbranch_scc1 .Lpq1_q1
	s_cmp_eq_u32 s98, 2
	s_cbranch_scc1 .Lpq1_q2
	s_cmp_eq_u32 s98, 3
	s_cbranch_scc1 .Lpq1_q3
	s_branch .Lpq1_end
.Lpq1_q0:
	ds_read2st64_b32 v[40:41], v143 offset0:0 offset1:1
	ds_read2st64_b32 v[42:43], v143 offset0:2 offset1:3
	ds_read2st64_b32 v[44:45], v143 offset0:4 offset1:5
	ds_read2st64_b32 v[46:47], v143 offset0:6 offset1:7
	ds_read2st64_b32 v[48:49], v143 offset0:8 offset1:9
	ds_read2st64_b32 v[50:51], v143 offset0:10 offset1:11
	ds_read2st64_b32 v[52:53], v143 offset0:12 offset1:13
	ds_read2st64_b32 v[54:55], v143 offset0:14 offset1:15
	ds_read2st64_b32 v[56:57], v143 offset0:16 offset1:17
	ds_read2st64_b32 v[58:59], v143 offset0:18 offset1:19
	ds_read2st64_b32 v[60:61], v143 offset0:20 offset1:21
	ds_read2st64_b32 v[62:63], v143 offset0:22 offset1:23
	v_lshrrev_b32_e32 v122, 1, v143
	v_mov_b32_e32 v69, 0
	s_waitcnt lgkmcnt(11)
	v_add_f32_e32 v65, v69, v41
	s_waitcnt lgkmcnt(8)
	v_add_f32_e32 v66, v65, v47
	s_waitcnt lgkmcnt(5)
	v_add_f32_e32 v67, v66, v53
	s_waitcnt lgkmcnt(2)
	v_add_f32_e32 v68, v67, v59
	v_mul_f32_e32 v79, 0xbfb8aa3b, v69
	v_exp_f32_e32 v70, v79
	v_mul_f32_e32 v80, 0xbfb8aa3b, v65
	v_exp_f32_e32 v71, v80
	v_mul_f32_e32 v79, 0x3fb8aa3b, v65
	v_exp_f32_e32 v75, v79
	v_mul_f32_e32 v80, 0xbfb8aa3b, v66
	v_exp_f32_e32 v72, v80
	v_mul_f32_e32 v79, 0x3fb8aa3b, v66
	v_exp_f32_e32 v76, v79
	v_mul_f32_e32 v80, 0xbfb8aa3b, v67
	v_exp_f32_e32 v73, v80
	v_mul_f32_e32 v79, 0x3fb8aa3b, v67
	v_exp_f32_e32 v77, v79
	v_mul_f32_e32 v80, 0xbfb8aa3b, v68
	v_exp_f32_e32 v74, v80
	v_mul_f32_e32 v79, 0x3fb8aa3b, v68
	v_exp_f32_e32 v78, v79
	s_nop 0
	v_mul_f32_e32 v81, v70, v40
	v_mul_f32_e32 v85, v75, v43
	v_mul_f32_e32 v89, v75, v42
	v_mul_f32_e32 v93, v71, v44
	v_mul_f32_e32 v82, v71, v46
	v_mul_f32_e32 v86, v76, v49
	v_mul_f32_e32 v90, v76, v48
	v_mul_f32_e32 v94, v72, v50
	v_mul_f32_e32 v83, v72, v52
	v_mul_f32_e32 v87, v77, v55
	v_mul_f32_e32 v91, v77, v54
	v_mul_f32_e32 v95, v73, v56
	v_mul_f32_e32 v84, v73, v58
	s_waitcnt lgkmcnt(1)
	v_mul_f32_e32 v88, v78, v61
	v_mul_f32_e32 v92, v78, v60
	s_waitcnt lgkmcnt(0)
	v_mul_f32_e32 v96, v74, v62
	v_cvt_pk_bf16_f32 v112, v81, v82
	v_cvt_pk_bf16_f32 v113, v83, v84
	v_cvt_pk_bf16_f32 v114, v85, v86
	v_cvt_pk_bf16_f32 v115, v87, v88
	v_cvt_pk_bf16_f32 v116, v89, v90
	v_cvt_pk_bf16_f32 v117, v91, v92
	v_cvt_pk_bf16_f32 v118, v93, v94
	v_cvt_pk_bf16_f32 v119, v95, v96
	v_cvt_pk_bf16_f32 v120, v45, v51
	v_cvt_pk_bf16_f32 v121, v57, v63
	ds_write_b16 v122, v112 offset:49152
	ds_write_b16_d16_hi v122, v112 offset:49296
	ds_write_b16 v122, v113 offset:49440
	ds_write_b16_d16_hi v122, v113 offset:49584
	ds_write_b16 v122, v114 offset:53760
	ds_write_b16_d16_hi v122, v114 offset:53904
	ds_write_b16 v122, v115 offset:54048
	ds_write_b16_d16_hi v122, v115 offset:54192
	ds_write_b16 v122, v116 offset:56064
	ds_write_b16_d16_hi v122, v116 offset:56208
	ds_write_b16 v122, v117 offset:56352
	ds_write_b16_d16_hi v122, v117 offset:56496
	ds_write_b16 v122, v118 offset:58368
	ds_write_b16_d16_hi v122, v118 offset:58512
	ds_write_b16 v122, v119 offset:58656
	ds_write_b16_d16_hi v122, v119 offset:58800
	ds_write_b64 v139, v[114:115] offset:0
	ds_write_b64 v139, v[116:117] offset:32
	ds_write_b64 v140, v[120:121] offset:32
	s_branch .Lpq1_end
.Lpq1_q1:
	ds_read2st64_b32 v[26:27], v143 offset0:1 offset1:7
	ds_read2st64_b32 v[28:29], v143 offset0:13 offset1:19
	ds_read2st64_b32 v[40:41], v143 offset0:24 offset1:25
	ds_read2st64_b32 v[42:43], v143 offset0:26 offset1:27
	ds_read2st64_b32 v[44:45], v143 offset0:28 offset1:29
	ds_read2st64_b32 v[46:47], v143 offset0:30 offset1:31
	ds_read2st64_b32 v[48:49], v143 offset0:32 offset1:33
	ds_read2st64_b32 v[50:51], v143 offset0:34 offset1:35
	ds_read2st64_b32 v[52:53], v143 offset0:36 offset1:37
	ds_read2st64_b32 v[54:55], v143 offset0:38 offset1:39
	ds_read2st64_b32 v[56:57], v143 offset0:40 offset1:41
	ds_read2st64_b32 v[58:59], v143 offset0:42 offset1:43
	ds_read2st64_b32 v[60:61], v143 offset0:44 offset1:45
	ds_read2st64_b32 v[62:63], v143 offset0:46 offset1:47
	v_lshrrev_b32_e32 v122, 1, v143
	s_waitcnt lgkmcnt(13)
	v_add_f32_e32 v69, v26, v27
	s_waitcnt lgkmcnt(12)
	v_add_f32_e32 v69, v69, v28
	v_add_f32_e32 v69, v69, v29
	s_waitcnt lgkmcnt(11)
	v_add_f32_e32 v65, v69, v41
	s_waitcnt lgkmcnt(8)
	v_add_f32_e32 v66, v65, v47
	s_waitcnt lgkmcnt(5)
	v_add_f32_e32 v67, v66, v53
	s_waitcnt lgkmcnt(2)
	v_add_f32_e32 v68, v67, v59
	v_mul_f32_e32 v79, 0xbfb8aa3b, v69
	v_exp_f32_e32 v70, v79
	v_mul_f32_e32 v80, 0xbfb8aa3b, v65
	v_exp_f32_e32 v71, v80
	v_mul_f32_e32 v79, 0x3fb8aa3b, v65
	v_exp_f32_e32 v75, v79
	v_mul_f32_e32 v80, 0xbfb8aa3b, v66
	v_exp_f32_e32 v72, v80
	v_mul_f32_e32 v79, 0x3fb8aa3b, v66
	v_exp_f32_e32 v76, v79
	v_mul_f32_e32 v80, 0xbfb8aa3b, v67
	v_exp_f32_e32 v73, v80
	v_mul_f32_e32 v79, 0x3fb8aa3b, v67
	v_exp_f32_e32 v77, v79
	v_mul_f32_e32 v80, 0xbfb8aa3b, v68
	v_exp_f32_e32 v74, v80
	v_mul_f32_e32 v79, 0x3fb8aa3b, v68
	v_exp_f32_e32 v78, v79
	s_nop 0
	v_mul_f32_e32 v81, v70, v40
	v_mul_f32_e32 v85, v75, v43
	v_mul_f32_e32 v89, v75, v42
	v_mul_f32_e32 v93, v71, v44
	v_mul_f32_e32 v82, v71, v46
	v_mul_f32_e32 v86, v76, v49
	v_mul_f32_e32 v90, v76, v48
	v_mul_f32_e32 v94, v72, v50
	v_mul_f32_e32 v83, v72, v52
	v_mul_f32_e32 v87, v77, v55
	v_mul_f32_e32 v91, v77, v54
	v_mul_f32_e32 v95, v73, v56
	v_mul_f32_e32 v84, v73, v58
	s_waitcnt lgkmcnt(1)
	v_mul_f32_e32 v88, v78, v61
	v_mul_f32_e32 v92, v78, v60
	s_waitcnt lgkmcnt(0)
	v_mul_f32_e32 v96, v74, v62
	v_cvt_pk_bf16_f32 v112, v81, v82
	v_cvt_pk_bf16_f32 v113, v83, v84
	v_cvt_pk_bf16_f32 v114, v85, v86
	v_cvt_pk_bf16_f32 v115, v87, v88
	v_cvt_pk_bf16_f32 v116, v89, v90
	v_cvt_pk_bf16_f32 v117, v91, v92
	v_cvt_pk_bf16_f32 v118, v93, v94
	v_cvt_pk_bf16_f32 v119, v95, v96
	v_cvt_pk_bf16_f32 v120, v45, v51
	v_cvt_pk_bf16_f32 v121, v57, v63
	ds_write_b16 v122, v112 offset:49728
	ds_write_b16_d16_hi v122, v112 offset:49872
	ds_write_b16 v122, v113 offset:50016
	ds_write_b16_d16_hi v122, v113 offset:50160
	ds_write_b16 v122, v114 offset:54336
	ds_write_b16_d16_hi v122, v114 offset:54480
	ds_write_b16 v122, v115 offset:54624
	ds_write_b16_d16_hi v122, v115 offset:54768
	ds_write_b16 v122, v116 offset:56640
	ds_write_b16_d16_hi v122, v116 offset:56784
	ds_write_b16 v122, v117 offset:56928
	ds_write_b16_d16_hi v122, v117 offset:57072
	ds_write_b16 v122, v118 offset:58944
	ds_write_b16_d16_hi v122, v118 offset:59088
	ds_write_b16 v122, v119 offset:59232
	ds_write_b16_d16_hi v122, v119 offset:59376
	ds_write_b64 v139, v[114:115] offset:8
	ds_write_b64 v139, v[116:117] offset:40
	ds_write_b64 v140, v[120:121] offset:40
	s_branch .Lpq1_end
.Lpq1_q2:
	ds_read2st64_b32 v[26:27], v143 offset0:1 offset1:7
	ds_read2st64_b32 v[28:29], v143 offset0:13 offset1:19
	ds_read2st64_b32 v[30:31], v143 offset0:25 offset1:31
	ds_read2st64_b32 v[32:33], v143 offset0:37 offset1:43
	ds_read2st64_b32 v[40:41], v143 offset0:48 offset1:49
	ds_read2st64_b32 v[42:43], v143 offset0:50 offset1:51
	ds_read2st64_b32 v[44:45], v143 offset0:52 offset1:53
	ds_read2st64_b32 v[46:47], v143 offset0:54 offset1:55
	ds_read2st64_b32 v[48:49], v143 offset0:56 offset1:57
	ds_read2st64_b32 v[50:51], v143 offset0:58 offset1:59
	ds_read2st64_b32 v[52:53], v143 offset0:60 offset1:61
	ds_read2st64_b32 v[54:55], v143 offset0:62 offset1:63
	ds_read2st64_b32 v[56:57], v143 offset0:64 offset1:65
	ds_read2st64_b32 v[58:59], v143 offset0:66 offset1:67
	ds_read2st64_b32 v[60:61], v143 offset0:68 offset1:69
	s_waitcnt lgkmcnt(14)
	ds_read2st64_b32 v[62:63], v143 offset0:70 offset1:71
	v_lshrrev_b32_e32 v122, 1, v143
	v_add_f32_e32 v69, v26, v27
	s_waitcnt lgkmcnt(14)
	v_add_f32_e32 v69, v69, v28
	v_add_f32_e32 v69, v69, v29
	s_waitcnt lgkmcnt(13)
	v_add_f32_e32 v69, v69, v30
	v_add_f32_e32 v69, v69, v31
	s_waitcnt lgkmcnt(12)
	v_add_f32_e32 v69, v69, v32
	v_add_f32_e32 v69, v69, v33
	s_waitcnt lgkmcnt(11)
	v_add_f32_e32 v65, v69, v41
	s_waitcnt lgkmcnt(8)
	v_add_f32_e32 v66, v65, v47
	s_waitcnt lgkmcnt(5)
	v_add_f32_e32 v67, v66, v53
	s_waitcnt lgkmcnt(2)
	v_add_f32_e32 v68, v67, v59
	v_mul_f32_e32 v79, 0xbfb8aa3b, v69
	v_exp_f32_e32 v70, v79
	v_mul_f32_e32 v80, 0xbfb8aa3b, v65
	v_exp_f32_e32 v71, v80
	v_mul_f32_e32 v79, 0x3fb8aa3b, v65
	v_exp_f32_e32 v75, v79
	v_mul_f32_e32 v80, 0xbfb8aa3b, v66
	v_exp_f32_e32 v72, v80
	v_mul_f32_e32 v79, 0x3fb8aa3b, v66
	v_exp_f32_e32 v76, v79
	v_mul_f32_e32 v80, 0xbfb8aa3b, v67
	v_exp_f32_e32 v73, v80
	v_mul_f32_e32 v79, 0x3fb8aa3b, v67
	v_exp_f32_e32 v77, v79
	v_mul_f32_e32 v80, 0xbfb8aa3b, v68
	v_exp_f32_e32 v74, v80
	v_mul_f32_e32 v79, 0x3fb8aa3b, v68
	v_exp_f32_e32 v78, v79
	s_nop 0
	v_mul_f32_e32 v81, v70, v40
	v_mul_f32_e32 v85, v75, v43
	v_mul_f32_e32 v89, v75, v42
	v_mul_f32_e32 v93, v71, v44
	v_mul_f32_e32 v82, v71, v46
	v_mul_f32_e32 v86, v76, v49
	v_mul_f32_e32 v90, v76, v48
	v_mul_f32_e32 v94, v72, v50
	v_mul_f32_e32 v83, v72, v52
	v_mul_f32_e32 v87, v77, v55
	v_mul_f32_e32 v91, v77, v54
	v_mul_f32_e32 v95, v73, v56
	v_mul_f32_e32 v84, v73, v58
	s_waitcnt lgkmcnt(1)
	v_mul_f32_e32 v88, v78, v61
	v_mul_f32_e32 v92, v78, v60
	s_waitcnt lgkmcnt(0)
	v_mul_f32_e32 v96, v74, v62
	v_cvt_pk_bf16_f32 v112, v81, v82
	v_cvt_pk_bf16_f32 v113, v83, v84
	v_cvt_pk_bf16_f32 v114, v85, v86
	v_cvt_pk_bf16_f32 v115, v87, v88
	v_cvt_pk_bf16_f32 v116, v89, v90
	v_cvt_pk_bf16_f32 v117, v91, v92
	v_cvt_pk_bf16_f32 v118, v93, v94
	v_cvt_pk_bf16_f32 v119, v95, v96
	v_cvt_pk_bf16_f32 v120, v45, v51
	v_cvt_pk_bf16_f32 v121, v57, v63
	ds_write_b16 v122, v112 offset:50304
	ds_write_b16_d16_hi v122, v112 offset:50448
	ds_write_b16 v122, v113 offset:50592
	ds_write_b16_d16_hi v122, v113 offset:50736
	ds_write_b16 v122, v114 offset:54912
	ds_write_b16_d16_hi v122, v114 offset:55056
	ds_write_b16 v122, v115 offset:55200
	ds_write_b16_d16_hi v122, v115 offset:55344
	ds_write_b16 v122, v116 offset:57216
	ds_write_b16_d16_hi v122, v116 offset:57360
	ds_write_b16 v122, v117 offset:57504
	ds_write_b16_d16_hi v122, v117 offset:57648
	ds_write_b16 v122, v118 offset:59520
	ds_write_b16_d16_hi v122, v118 offset:59664
	ds_write_b16 v122, v119 offset:59808
	ds_write_b16_d16_hi v122, v119 offset:59952
	ds_write_b64 v139, v[114:115] offset:16
	ds_write_b64 v139, v[116:117] offset:48
	ds_write_b64 v140, v[120:121] offset:48
	s_branch .Lpq1_end
.Lpq1_q3:
	ds_read2st64_b32 v[26:27], v143 offset0:1 offset1:7
	ds_read2st64_b32 v[28:29], v143 offset0:13 offset1:19
	ds_read2st64_b32 v[30:31], v143 offset0:25 offset1:31
	ds_read2st64_b32 v[32:33], v143 offset0:37 offset1:43
	ds_read2st64_b32 v[34:35], v143 offset0:49 offset1:55
	ds_read2st64_b32 v[36:37], v143 offset0:61 offset1:67
	ds_read2st64_b32 v[40:41], v143 offset0:72 offset1:73
	ds_read2st64_b32 v[42:43], v143 offset0:74 offset1:75
	ds_read2st64_b32 v[44:45], v143 offset0:76 offset1:77
	ds_read2st64_b32 v[46:47], v143 offset0:78 offset1:79
	ds_read2st64_b32 v[48:49], v143 offset0:80 offset1:81
	ds_read2st64_b32 v[50:51], v143 offset0:82 offset1:83
	ds_read2st64_b32 v[52:53], v143 offset0:84 offset1:85
	ds_read2st64_b32 v[54:55], v143 offset0:86 offset1:87
	ds_read2st64_b32 v[56:57], v143 offset0:88 offset1:89
	s_waitcnt lgkmcnt(14)
	ds_read2st64_b32 v[58:59], v143 offset0:90 offset1:91
	s_waitcnt lgkmcnt(14)
	ds_read2st64_b32 v[60:61], v143 offset0:92 offset1:93
	s_waitcnt lgkmcnt(14)
	ds_read2st64_b32 v[62:63], v143 offset0:94 offset1:95
	v_lshrrev_b32_e32 v122, 1, v143
	v_add_f32_e32 v69, v26, v27
	v_add_f32_e32 v69, v69, v28
	v_add_f32_e32 v69, v69, v29
	v_add_f32_e32 v69, v69, v30
	v_add_f32_e32 v69, v69, v31
	s_waitcnt lgkmcnt(14)
	v_add_f32_e32 v69, v69, v32
	v_add_f32_e32 v69, v69, v33
	s_waitcnt lgkmcnt(13)
	v_add_f32_e32 v69, v69, v34
	v_add_f32_e32 v69, v69, v35
	s_waitcnt lgkmcnt(12)
	v_add_f32_e32 v69, v69, v36
	v_add_f32_e32 v69, v69, v37
	s_waitcnt lgkmcnt(11)
	v_add_f32_e32 v65, v69, v41
	s_waitcnt lgkmcnt(8)
	v_add_f32_e32 v66, v65, v47
	s_waitcnt lgkmcnt(5)
	v_add_f32_e32 v67, v66, v53
	s_waitcnt lgkmcnt(2)
	v_add_f32_e32 v68, v67, v59
	v_mul_f32_e32 v79, 0xbfb8aa3b, v69
	v_exp_f32_e32 v70, v79
	v_mul_f32_e32 v80, 0xbfb8aa3b, v65
	v_exp_f32_e32 v71, v80
	v_mul_f32_e32 v79, 0x3fb8aa3b, v65
	v_exp_f32_e32 v75, v79
	v_mul_f32_e32 v80, 0xbfb8aa3b, v66
	v_exp_f32_e32 v72, v80
	v_mul_f32_e32 v79, 0x3fb8aa3b, v66
	v_exp_f32_e32 v76, v79
	v_mul_f32_e32 v80, 0xbfb8aa3b, v67
	v_exp_f32_e32 v73, v80
	v_mul_f32_e32 v79, 0x3fb8aa3b, v67
	v_exp_f32_e32 v77, v79
	v_mul_f32_e32 v80, 0xbfb8aa3b, v68
	v_exp_f32_e32 v74, v80
	v_mul_f32_e32 v79, 0x3fb8aa3b, v68
	v_exp_f32_e32 v78, v79
	s_nop 0
	v_mul_f32_e32 v81, v70, v40
	v_mul_f32_e32 v85, v75, v43
	v_mul_f32_e32 v89, v75, v42
	v_mul_f32_e32 v93, v71, v44
	v_mul_f32_e32 v82, v71, v46
	v_mul_f32_e32 v86, v76, v49
	v_mul_f32_e32 v90, v76, v48
	v_mul_f32_e32 v94, v72, v50
	v_mul_f32_e32 v83, v72, v52
	v_mul_f32_e32 v87, v77, v55
	v_mul_f32_e32 v91, v77, v54
	v_mul_f32_e32 v95, v73, v56
	v_mul_f32_e32 v84, v73, v58
	s_waitcnt lgkmcnt(1)
	v_mul_f32_e32 v88, v78, v61
	v_mul_f32_e32 v92, v78, v60
	s_waitcnt lgkmcnt(0)
	v_mul_f32_e32 v96, v74, v62
	v_cvt_pk_bf16_f32 v112, v81, v82
	v_cvt_pk_bf16_f32 v113, v83, v84
	v_cvt_pk_bf16_f32 v114, v85, v86
	v_cvt_pk_bf16_f32 v115, v87, v88
	v_cvt_pk_bf16_f32 v116, v89, v90
	v_cvt_pk_bf16_f32 v117, v91, v92
	v_cvt_pk_bf16_f32 v118, v93, v94
	v_cvt_pk_bf16_f32 v119, v95, v96
	v_cvt_pk_bf16_f32 v120, v45, v51
	v_cvt_pk_bf16_f32 v121, v57, v63
	ds_write_b16 v122, v112 offset:50880
	ds_write_b16_d16_hi v122, v112 offset:51024
	ds_write_b16 v122, v113 offset:51168
	ds_write_b16_d16_hi v122, v113 offset:51312
	ds_write_b16 v122, v114 offset:55488
	ds_write_b16_d16_hi v122, v114 offset:55632
	ds_write_b16 v122, v115 offset:55776
	ds_write_b16_d16_hi v122, v115 offset:55920
	ds_write_b16 v122, v116 offset:57792
	ds_write_b16_d16_hi v122, v116 offset:57936
	ds_write_b16 v122, v117 offset:58080
	ds_write_b16_d16_hi v122, v117 offset:58224
	ds_write_b16 v122, v118 offset:60096
	ds_write_b16_d16_hi v122, v118 offset:60240
	ds_write_b16 v122, v119 offset:60384
	ds_write_b16_d16_hi v122, v119 offset:60528
	ds_write_b64 v139, v[114:115] offset:24
	ds_write_b64 v139, v[116:117] offset:56
	ds_write_b64 v140, v[120:121] offset:56
	v_add_u32_e32 v123, 0x18d00, v143
	ds_write_b32 v123, v74
	s_branch .Lpq1_end
.Lpq1_end:
	s_waitcnt lgkmcnt(0)
	s_barrier
	s_and_b64 s[24:25], s[46:47], s[2:3]
	ds_read_b128 v[48:51], v180 offset:5120
	ds_read_b128 v[52:55], v170 offset:5120
	ds_read_b128 v[56:59], v170 offset:6400
	v_sub_u32_e32 v113, v164, v143
	v_mad_u32_u24 v113, v145, 5, v113
	v_add_u32_e32 v113, 0x18e00, v113
	ds_read_b128 v[88:91], v113
	ds_read_b128 v[92:95], v113 offset:64
	v_mul_u32_u24_e32 v114, 5, v145
	v_sub_u32_e32 v114, v143, v114
	v_mul_i32_i24_e32 v114, 0x47, v114
	v_ashrrev_i32_e32 v114, 1, v114
	v_add_u32_e32 v114, v181, v114
	s_and_saveexec_b64 s[74:75], s[56:57]
	s_cbranch_execz .Lsy1_r1
	ds_read_b128 v[62:65], v175 offset:5120
	ds_read_b128 v[66:69], v200 offset:1280

.Lsy1_r2:
	s_or_b64 exec, exec, s[74:75]
	s_waitcnt lgkmcnt(2)
	v_mfma_f32_16x16x32_bf16 v[14:17], v[52:55], v[48:51], v[14:17]
	v_mfma_f32_16x16x32_bf16 v[18:21], v[56:59], v[48:51], v[18:21]
	s_and_saveexec_b64 s[74:75], s[56:57]
	s_cbranch_execz .Lsy1_m1
	s_waitcnt lgkmcnt(0)
	v_mfma_f32_16x16x32_bf16 v[22:25], v[62:65], v[66:69], v[22:25]

.Lsy1_m2:
	s_or_b64 exec, exec, s[74:75]
	s_waitcnt lgkmcnt(0)
	s_nop 1
	v_pk_mul_f32 v[14:15], v[14:15], v[88:89]
	v_pk_mul_f32 v[16:17], v[16:17], v[90:91]
	v_pk_mul_f32 v[18:19], v[18:19], v[92:93]
	v_pk_mul_f32 v[20:21], v[20:21], v[94:95]
	v_cvt_pk_bf16_f32 v116, v14, v15
	v_cvt_pk_bf16_f32 v117, v16, v17
	v_cvt_pk_bf16_f32 v118, v18, v19
	v_cvt_pk_bf16_f32 v119, v20, v21
	ds_write_b64 v114, v[116:117]
	ds_write_b64 v114, v[118:119] offset:32
	s_and_saveexec_b64 s[74:75], s[56:57]
	s_cbranch_execz .Lsy1_w1
	ds_write_b128 v179, v[22:25] offset:4096
